# norm phases: waves owning a context row prefetch all split-K partial lines at phase entry so the serialized fold loads hit L2
# baseline (speedup 1.0000x reference)
.LBB0_216:
	s_waitcnt lgkmcnt(0)
	v_readlane_b32 s12, v251, 0
	s_cmp_eq_u32 s78, 0
	v_readlane_b32 s16, v251, 4
	v_readlane_b32 s17, v251, 5
	v_readlane_b32 s20, v251, 8
	v_readlane_b32 s21, v251, 9
	s_cselect_b64 s[2:3], -1, 0
	s_cmp_lg_u32 s78, 0
	v_readlane_b32 s0, v251, 36
	s_mov_b64 s[16:17], s[20:21]
	s_cselect_b64 s[4:5], -1, 0
	s_add_u32 s8, s16, s79
	v_lshl_add_u32 v60, s0, 6, v220
	s_addc_u32 s9, s17, 0
	v_readlane_b32 s0, v251, 34
	v_readlane_b32 s1, v251, 35
	s_add_u32 s0, s0, s82
	s_waitcnt vmcnt(0)
	v_lshlrev_b32_e32 v0, 3, v60
	s_addc_u32 s1, s1, 0
	v_and_b32_e32 v42, 0x1f8, v0
	s_mov_b32 s10, s91
	s_add_u32 s6, s0, 0x1000
	v_lshlrev_b32_e32 v74, 2, v42
	s_addc_u32 s7, s1, 0
	v_readlane_b32 s42, v251, 36
	s_lshl_b32 s43, s91, 3
	s_add_i32 s42, s42, s43
	s_cmp_gt_u32 s42, 255
	s_cbranch_scc1 .Lnpf0
	v_readlane_b32 s43, v255, 45
	s_cmp_eq_u32 s43, 0
	s_cbranch_scc1 .Lnpf0
	v_readlane_b32 s44, v252, 11
	v_readlane_b32 s45, v252, 12
	s_lshl_b32 s42, s42, 12
	s_add_u32 s44, s44, s42
	s_addc_u32 s45, s45, 0
	v_lshlrev_b32_e32 v199, 6, v220
	global_load_dword v200, v199, s[44:45]
	s_add_u32 s44, s44, 0x100000
	s_addc_u32 s45, s45, 0
	global_load_dword v201, v199, s[44:45]
	s_add_u32 s44, s44, 0x100000
	s_addc_u32 s45, s45, 0
	global_load_dword v202, v199, s[44:45]
	s_add_u32 s44, s44, 0x100000
	s_addc_u32 s45, s45, 0
	global_load_dword v203, v199, s[44:45]
	s_add_u32 s44, s44, 0x100000
	s_addc_u32 s45, s45, 0
	global_load_dword v204, v199, s[44:45]
	s_add_u32 s44, s44, 0x100000
	s_addc_u32 s45, s45, 0
	global_load_dword v205, v199, s[44:45]
	s_add_u32 s44, s44, 0x100000
	s_addc_u32 s45, s45, 0
	global_load_dword v206, v199, s[44:45]
	s_add_u32 s44, s44, 0x100000
	s_addc_u32 s45, s45, 0
	global_load_dword v207, v199, s[44:45]
	s_add_u32 s44, s44, 0x100000
	s_addc_u32 s45, s45, 0
	global_load_dword v208, v199, s[44:45]
	s_add_u32 s44, s44, 0x100000
	s_addc_u32 s45, s45, 0
	global_load_dword v209, v199, s[44:45]
	s_add_u32 s44, s44, 0x100000
	s_addc_u32 s45, s45, 0
	global_load_dword v210, v199, s[44:45]
.Lnpf0:
	global_load_dwordx4 v[12:15], v74, s[8:9] offset:16
	global_load_dwordx4 v[50:53], v74, s[8:9]
	global_load_dwordx4 v[38:41], v74, s[6:7] offset:16
	global_load_dwordx4 v[54:57], v74, s[6:7]
	global_load_dwordx4 v[16:19], v74, s[0:1] offset:16
	global_load_dwordx4 v[20:23], v74, s[0:1]
	s_waitcnt vmcnt(16)
	v_or_b32_e32 v4, 0x200, v42
	v_lshlrev_b32_e32 v32, 2, v4
	global_load_dwordx4 v[0:3], v74, s[8:9] offset:2064
	global_load_dwordx4 v[8:11], v74, s[8:9] offset:2048
	global_load_dwordx4 v[4:7], v32, s[6:7] offset:16
	global_load_dwordx4 v[34:37], v32, s[6:7]
	global_load_dwordx4 v[24:27], v74, s[0:1] offset:2064
	global_load_dwordx4 v[28:31], v74, s[0:1] offset:2048
	v_ashrrev_i32_e32 v43, 6, v60
	v_lshl_add_u32 v58, s10, 3, v43
	s_movk_i32 s6, 0x4100
	v_readlane_b32 s22, v251, 10
	v_cmp_gt_i32_e32 vcc, s6, v58
	s_mov_b32 s22, s97
	s_and_b64 s[10:11], s[4:5], vcc
	v_ashrrev_i32_e32 v59, 31, v58
	v_lshlrev_b32_e32 v76, 1, v42
	v_readlane_b32 s13, v251, 1
	v_readlane_b32 s14, v251, 2
	v_readlane_b32 s15, v251, 3
	v_readlane_b32 s18, v251, 6
	v_readlane_b32 s19, v251, 7
	v_readlane_b32 s23, v251, 11
	v_readlane_b32 s24, v251, 12
	v_readlane_b32 s25, v251, 13
	v_readlane_b32 s26, v251, 14
	v_readlane_b32 s27, v251, 15
	s_and_saveexec_b64 s[6:7], s[10:11]
	s_cbranch_execz .LBB0_218
	v_readlane_b32 s12, v252, 26
	v_lshlrev_b64 v[42:43], 11, v[58:59]
	v_readlane_b32 s18, v252, 32
	v_readlane_b32 s19, v252, 33
	v_mov_b32_e32 v77, v33
	v_readlane_b32 s13, v252, 27
	v_lshl_add_u64 v[42:43], s[18:19], 0, v[42:43]
	v_lshl_add_u64 v[42:43], v[42:43], 0, v[76:77]
	global_load_dwordx4 v[46:49], v[42:43], off
	s_nop 0
	global_load_dwordx4 v[42:45], v[42:43], off offset:1024
	v_readlane_b32 s14, v252, 28
	v_readlane_b32 s15, v252, 29
	v_readlane_b32 s16, v252, 30
	v_readlane_b32 s17, v252, 31

.LBB0_305:
	v_readlane_b32 s0, v251, 36
	v_readlane_b32 s2, v252, 54
	v_readlane_b32 s6, v252, 58
	v_lshl_add_u32 v64, s0, 6, v220
	v_readlane_b32 s4, v252, 56
	s_waitcnt vmcnt(0)
	v_lshlrev_b32_e32 v0, 3, v64
	v_and_b32_e32 v32, 0x1f8, v0
	s_waitcnt vmcnt(4)
	v_or_b32_e32 v8, 0x200, v32
	s_mov_b32 s0, s91
	v_lshlrev_b32_e32 v60, 2, v32
	v_readlane_b32 s3, v252, 55
	v_readlane_b32 s7, v252, 59
	v_readlane_b32 s5, v252, 57
	v_lshlrev_b32_e32 v62, 2, v8
	s_nop 1
	v_readlane_b32 s42, v251, 36
	s_lshl_b32 s43, s91, 3
	s_add_i32 s42, s42, s43
	s_cmp_gt_u32 s42, 255
	s_cbranch_scc1 .Lnpf1
	v_readlane_b32 s44, v252, 11
	v_readlane_b32 s45, v252, 12
	s_lshl_b32 s42, s42, 12
	s_add_u32 s44, s44, s42
	s_addc_u32 s45, s45, 0
	v_lshlrev_b32_e32 v199, 6, v220
	global_load_dword v200, v199, s[44:45]
	s_add_u32 s44, s44, 0x100000
	s_addc_u32 s45, s45, 0
	global_load_dword v201, v199, s[44:45]
	s_add_u32 s44, s44, 0x100000
	s_addc_u32 s45, s45, 0
	global_load_dword v202, v199, s[44:45]
	s_add_u32 s44, s44, 0x100000
	s_addc_u32 s45, s45, 0
	global_load_dword v203, v199, s[44:45]
	s_add_u32 s44, s44, 0x100000
	s_addc_u32 s45, s45, 0
	global_load_dword v204, v199, s[44:45]
	s_add_u32 s44, s44, 0x100000
	s_addc_u32 s45, s45, 0
	global_load_dword v205, v199, s[44:45]
	s_add_u32 s44, s44, 0x100000
	s_addc_u32 s45, s45, 0
	global_load_dword v206, v199, s[44:45]
	s_add_u32 s44, s44, 0x100000
	s_addc_u32 s45, s45, 0
	global_load_dword v207, v199, s[44:45]
	s_add_u32 s44, s44, 0x100000
	s_addc_u32 s45, s45, 0
	global_load_dword v208, v199, s[44:45]
	s_add_u32 s44, s44, 0x100000
	s_addc_u32 s45, s45, 0
	global_load_dword v209, v199, s[44:45]
	s_add_u32 s44, s44, 0x100000
	s_addc_u32 s45, s45, 0
	global_load_dword v210, v199, s[44:45]
.Lnpf1:
	global_load_dwordx4 v[20:23], v60, s[2:3] offset:16
	global_load_dwordx4 v[50:53], v60, s[2:3]
	global_load_dwordx4 v[46:49], v60, s[6:7] offset:16
	global_load_dwordx4 v[54:57], v60, s[6:7]
	global_load_dwordx4 v[0:3], v60, s[4:5] offset:16
	global_load_dwordx4 v[4:7], v60, s[4:5]
	global_load_dwordx4 v[16:19], v62, s[2:3] offset:16
	global_load_dwordx4 v[38:41], v62, s[2:3]
	global_load_dwordx4 v[34:37], v62, s[6:7] offset:16
	global_load_dwordx4 v[42:45], v62, s[6:7]
	global_load_dwordx4 v[8:11], v62, s[4:5] offset:16
	global_load_dwordx4 v[12:15], v62, s[4:5]
	s_waitcnt vmcnt(13)
	v_ashrrev_i32_e32 v24, 6, v64
	v_lshl_add_u32 v58, s0, 3, v24
	s_movk_i32 s0, 0x4100
	v_cmp_gt_i32_e32 vcc, s0, v58
	v_ashrrev_i32_e32 v59, 31, v58
	s_and_saveexec_b64 s[0:1], vcc
	s_cbranch_execz .LBB0_307
	v_readlane_b32 s4, v252, 26
	v_lshlrev_b64 v[24:25], 11, v[58:59]
	v_readlane_b32 s10, v252, 32
	v_readlane_b32 s11, v252, 33
	v_lshlrev_b32_e32 v32, 1, v32
	v_readlane_b32 s5, v252, 27
	v_lshl_add_u64 v[24:25], s[10:11], 0, v[24:25]
	v_lshl_add_u64 v[24:25], v[24:25], 0, v[32:33]
	global_load_dwordx4 v[28:31], v[24:25], off
	s_nop 0
	global_load_dwordx4 v[24:27], v[24:25], off offset:1024
	v_readlane_b32 s6, v252, 28
	v_readlane_b32 s7, v252, 29
	v_readlane_b32 s8, v252, 30
	v_readlane_b32 s9, v252, 31

.LBB0_1181:
	v_readlane_b32 s0, v251, 36
	v_readlane_b32 s2, v254, 15
	v_readlane_b32 s6, v254, 19
	v_lshl_add_u32 v90, s0, 6, v220
	v_readlane_b32 s4, v254, 17
	s_waitcnt vmcnt(0)
	v_lshlrev_b32_e32 v0, 3, v90
	v_and_b32_e32 v24, 0x1f8, v0
	v_or_b32_e32 v8, 0x200, v24
	s_mov_b32 s0, s91
	v_lshlrev_b32_e32 v58, 2, v24
	v_readlane_b32 s3, v254, 16
	v_readlane_b32 s7, v254, 20
	v_readlane_b32 s5, v254, 18
	v_lshlrev_b32_e32 v88, 2, v8
	s_nop 1
	v_readlane_b32 s42, v251, 36
	s_lshl_b32 s43, s91, 3
	s_add_i32 s42, s42, s43
	s_cmp_gt_u32 s42, 255
	s_cbranch_scc1 .Lnpf2
	v_readlane_b32 s43, v255, 45
	s_cmp_gt_u32 s43, 2
	s_cbranch_scc1 .Lnpf2
	v_readlane_b32 s44, v252, 11
	v_readlane_b32 s45, v252, 12
	s_lshl_b32 s42, s42, 12
	s_add_u32 s44, s44, s42
	s_addc_u32 s45, s45, 0
	v_lshlrev_b32_e32 v199, 6, v220
	global_load_dword v200, v199, s[44:45]
	s_add_u32 s44, s44, 0x100000
	s_addc_u32 s45, s45, 0
	global_load_dword v201, v199, s[44:45]
	s_add_u32 s44, s44, 0x100000
	s_addc_u32 s45, s45, 0
	global_load_dword v202, v199, s[44:45]
	s_add_u32 s44, s44, 0x100000
	s_addc_u32 s45, s45, 0
	global_load_dword v203, v199, s[44:45]
	s_add_u32 s44, s44, 0x100000
	s_addc_u32 s45, s45, 0
	global_load_dword v204, v199, s[44:45]
	s_add_u32 s44, s44, 0x100000
	s_addc_u32 s45, s45, 0
	global_load_dword v205, v199, s[44:45]
	s_add_u32 s44, s44, 0x100000
	s_addc_u32 s45, s45, 0
	global_load_dword v206, v199, s[44:45]
	s_add_u32 s44, s44, 0x100000
	s_addc_u32 s45, s45, 0
	global_load_dword v207, v199, s[44:45]
.Lnpf2:
	global_load_dwordx4 v[20:23], v58, s[2:3] offset:16
	global_load_dwordx4 v[50:53], v58, s[2:3]
	global_load_dwordx4 v[46:49], v58, s[6:7] offset:16
	global_load_dwordx4 v[54:57], v58, s[6:7]
	global_load_dwordx4 v[0:3], v58, s[4:5] offset:16
	global_load_dwordx4 v[4:7], v58, s[4:5]
	global_load_dwordx4 v[16:19], v88, s[2:3] offset:16
	global_load_dwordx4 v[38:41], v88, s[2:3]
	global_load_dwordx4 v[34:37], v88, s[6:7] offset:16
	global_load_dwordx4 v[42:45], v88, s[6:7]
	global_load_dwordx4 v[8:11], v88, s[4:5] offset:16
	global_load_dwordx4 v[12:15], v88, s[4:5]
	v_ashrrev_i32_e32 v25, 6, v90
	v_lshl_add_u32 v112, s0, 3, v25
	s_movk_i32 s0, 0x4100
	v_cmp_gt_i32_e32 vcc, s0, v112
	v_ashrrev_i32_e32 v113, 31, v112
	v_lshlrev_b32_e32 v32, 1, v24
	s_and_saveexec_b64 s[0:1], vcc
	s_cbranch_execz .LBB0_1183
	v_readlane_b32 s4, v252, 26
	v_lshlrev_b64 v[24:25], 11, v[112:113]
	v_readlane_b32 s10, v252, 32
	v_readlane_b32 s11, v252, 33
	v_readlane_b32 s5, v252, 27
	v_readlane_b32 s6, v252, 28
	v_lshl_add_u64 v[24:25], s[10:11], 0, v[24:25]
	v_lshl_add_u64 v[24:25], v[24:25], 0, v[32:33]
	global_load_dwordx4 v[28:31], v[24:25], off
	s_nop 0
	global_load_dwordx4 v[24:27], v[24:25], off offset:1024
	v_readlane_b32 s7, v252, 29
	v_readlane_b32 s8, v252, 30
	v_readlane_b32 s9, v252, 31
